# v4: nb attention K/V tiles staged through private per-wave LDS (coalesced loads) + mixer A/B work rebalanced across WG halves
# speedup vs baseline: 1.3547x; 1.0664x over previous
.LBB0_162:
	s_andn2_b64 vcc, exec, s[6:7]
	s_cbranch_vccnz .LBB0_164
	s_cmpk_lt_i32 s58, 0x80
	s_cselect_b32 s0, 2, 1
.LBB0_164:
	s_add_u32 s6, s76, 0x3d00000
	s_addc_u32 s7, s77, 0
	s_add_u32 s8, s76, 0x9100000
	v_ashrrev_i32_e32 v101, 6, v100
	v_bfe_u32 v125, v100, 5, 1
	s_addc_u32 s9, s77, 0
	v_and_b32_e32 v124, 31, v100
	s_cmp_lt_i32 s0, 1
	v_lshlrev_b32_e32 v82, 4, v100
	v_lshlrev_b32_e32 v70, 5, v101
	v_lshlrev_b32_e32 v98, 4, v125
	s_cbranch_scc1 .LBB0_169
	v_cmp_lt_i32_e32 vcc, v183, v177
	s_lshl_b32 s1, s34, 18
	v_ashrrev_i32_e32 v30, 2, v100
	v_cndmask_b32_e32 v0, v176, v183, vcc
	v_cmp_lt_i32_e32 vcc, v182, v177
	v_lshlrev_b32_e32 v31, 2, v0
	s_add_u32 s10, s10, s1
	v_cndmask_b32_e32 v0, v176, v182, vcc
	v_lshlrev_b32_e32 v32, 2, v0
	v_and_b32_e32 v0, 0xffffffe0, v30
	s_addc_u32 s11, s11, 0
	v_ashrrev_i32_e32 v19, 31, v0
	v_or_b32_e32 v18, v0, v124
	v_lshlrev_b32_e32 v0, 5, v125
	v_lshl_add_u64 v[20:21], s[10:11], 0, v[0:1]
	v_and_b32_e32 v0, 32, v70
	s_lshl_b32 s30, s34, 9
	v_or_b32_e32 v3, v0, v124
	s_lshl_b64 s[12:13], s[30:31], 2
	v_and_b32_e32 v2, 48, v82
	v_mul_u32_u24_e32 v3, 0x110, v3
	s_add_u32 s4, s4, s12
	v_add3_u32 v33, 0, v3, v98
	v_lshl_or_b32 v4, v125, 2, v0
	v_mul_u32_u24_e32 v0, 0x110, v2
	v_lshlrev_b32_e32 v3, 1, v30
	s_addc_u32 s5, s5, s13
	s_mul_i32 s1, s58, 2
	s_add_i32 s2, s58, 0xffffff80
	s_mul_i32 s2, s2, 1
	s_addk_i32 s2, 0x100
	s_cmpk_lt_i32 s58, 0x80
	s_cselect_b32 s1, s1, s2
	s_mov_b32 s2, 0
	v_add3_u32 v34, 0, v0, v3
	v_lshlrev_b32_e32 v0, 1, v2
	v_lshlrev_b32_e32 v22, 1, v4
	s_branch .LBB0_167

.LBB0_169:
	s_cmpk_lt_i32 s58, 0x80
	v_readlane_b32 s80, v255, 0
	v_lshl_add_u32 v58, s58, 9, v100
	s_mov_b64 s[0:1], -1
	s_mov_b32 s2, 0x60000
	v_readlane_b32 s94, v255, 14
	v_readlane_b32 s95, v255, 15
	s_or_b64 s[0:1], s[42:43], s[0:1]
	v_cmp_gt_i32_e32 vcc, s2, v58
	s_mov_b64 s[10:11], s[94:95]
	s_and_b64 s[0:1], s[0:1], vcc
	v_readlane_b32 s81, v255, 1
	v_readlane_b32 s82, v255, 2
	v_readlane_b32 s83, v255, 3
	v_readlane_b32 s84, v255, 4
	v_readlane_b32 s85, v255, 5
	v_readlane_b32 s86, v255, 6
	v_readlane_b32 s87, v255, 7
	v_readlane_b32 s88, v255, 8
	v_readlane_b32 s89, v255, 9
	v_readlane_b32 s90, v255, 10
	v_readlane_b32 s91, v255, 11
	v_readlane_b32 s92, v255, 12
	v_readlane_b32 s93, v255, 13
	s_and_saveexec_b64 s[4:5], s[0:1]
	s_movk_i32 s20, 0x3ff
	v_readlane_b32 s30, v255, 61
	v_readlane_b32 s17, v255, 59
	v_readlane_b32 s21, v255, 60
	s_cbranch_execz .LBB0_176
	s_mul_i32 s30, s34, 0x300
	s_lshl_b64 s[0:1], s[30:31], 2
	s_add_u32 s10, s10, s0
	v_lshlrev_b32_e32 v0, 3, v100
	v_readlane_b32 s30, v255, 61
	v_readlane_b32 s21, v255, 60
	v_readlane_b32 s17, v255, 59
	s_mov_b32 s17, 0x20000
	s_mov_b32 s21, 0x100000
	s_addc_u32 s11, s11, s1
	v_lshl_add_u32 v59, s58, 12, v0
	s_mov_b64 s[74:75], 0
	s_branch .LBB0_172

.LBB0_218:
	v_cmp_lt_i32_e32 vcc, s20, v114
	s_or_b64 s[0:1], s[42:43], vcc
	s_and_saveexec_b64 s[82:83], s[0:1]
	s_cbranch_execz .LBB0_217
	v_lshlrev_b32_e32 v96, 1, v84
	s_and_saveexec_b64 s[0:1], vcc
	s_xor_b64 s[84:85], exec, s[0:1]
	s_cbranch_execz .LBB0_225
	v_lshrrev_b32_e32 v0, 5, v110
	v_and_b32_e32 v0, 0x7fffff0, v0
	v_bfe_u32 v120, v114, 7, 2
	v_readlane_b32 s0, v255, 37
	v_bfe_u32 v115, v114, 1, 6
	v_mov_b64_e32 v[2:3], s[6:7]
	v_add3_u32 v0, s0, v0, v120
	v_lshlrev_b64 v[104:105], 16, v[0:1]
	v_add_u32_e32 v0, 0xfffffc00, v114
	v_lshrrev_b32_e32 v121, 9, v0
	v_lshlrev_b32_e32 v0, 5, v114
	v_and_or_b32 v116, v0, 32, v124
	v_lshl_add_u32 v122, v121, 12, v187
	v_lshlrev_b32_e32 v0, 6, v115
	v_or3_b32 v0, v122, v0, v116
	v_mov_b64_e32 v[94:95], v[0:1]
	v_mad_u64_u32 v[102:103], s[0:1], v0, s19, v[2:3]
	v_lshlrev_b32_e32 v0, 7, v120
	v_lshl_add_u64 v[2:3], v[102:103], 0, v[0:1]
	v_mov_b32_e32 v97, v1
	v_lshl_add_u64 v[2:3], v[2:3], 0, v[96:97]
	s_mov_b64 s[0:1], 0x1400
	v_lshl_add_u64 v[4:5], v[2:3], 0, s[0:1]
	v_add_co_u32_e32 v2, vcc, s61, v2
	v_mov_b32_e32 v123, 0
	s_nop 0
	v_addc_co_u32_e32 v3, vcc, 0, v3, vcc
	global_load_dwordx4 v[50:53], v[4:5], off offset:32
	global_load_dwordx4 v[54:57], v[4:5], off offset:64
	global_load_dwordx4 v[58:61], v[2:3], off offset:1024
	global_load_dwordx4 v[62:65], v[4:5], off offset:96
	v_cmp_lt_i32_e32 vcc, v178, v177
	s_mov_b32 s0, 16
	v_lshlrev_b32_e32 v100, 6, v120
	v_cndmask_b32_e32 v0, v176, v178, vcc
	v_mov_b32_e32 v101, v1
	v_lshlrev_b32_e32 v117, 2, v0
	v_mov_b32_e32 v118, 0xf149f2ca
	v_mov_b64_e32 v[106:107], v[92:93]
	v_mov_b64_e32 v[108:109], v[90:91]
	v_mov_b32_e32 v18, 0
	v_mov_b32_e32 v19, v123
	v_mov_b32_e32 v20, v123
	v_mov_b32_e32 v21, v123
	v_mov_b32_e32 v22, v123
	v_mov_b32_e32 v23, v123
	v_mov_b32_e32 v24, v123
	v_mov_b32_e32 v25, v123
	v_mov_b32_e32 v26, v123
	v_mov_b32_e32 v27, v123
	v_mov_b32_e32 v28, v123
	v_mov_b32_e32 v29, v123
	v_mov_b32_e32 v30, v123
	v_mov_b32_e32 v31, v123
	v_mov_b32_e32 v32, v123
	v_mov_b32_e32 v33, v123
	v_mov_b32_e32 v2, 0
	v_mov_b32_e32 v3, v123
	v_mov_b32_e32 v4, v123
	v_mov_b32_e32 v5, v123
	v_mov_b32_e32 v6, v123
	v_mov_b32_e32 v7, v123
	v_mov_b32_e32 v8, v123
	v_mov_b32_e32 v9, v123
	v_mov_b32_e32 v10, v123
	v_mov_b32_e32 v11, v123
	v_mov_b32_e32 v12, v123
	v_mov_b32_e32 v13, v123
	v_mov_b32_e32 v14, v123
	v_mov_b32_e32 v15, v123
	v_mov_b32_e32 v16, v123
	v_mov_b32_e32 v17, v123
	v_lshrrev_b32_e32 v244, 6, v174
	v_mul_u32_u24_e32 v244, 0x2600, v244
	v_add_u32_e32 v244, 0x2000, v244
	v_lshrrev_b32_e32 v245, 3, v176
	v_mul_u32_u24_e32 v245, 0x90, v245
	v_and_b32_e32 v195, 7, v176
	v_lshl_add_u32 v245, v195, 4, v245
	v_add_u32_e32 v245, v245, v244
	v_lshrrev_b32_e32 v246, 2, v176
	v_mul_u32_u24_e32 v246, 0x50, v246
	v_and_b32_e32 v195, 3, v176
	v_lshl_add_u32 v246, v195, 4, v246
	v_add_u32_e32 v246, v246, v244
	v_add_u32_e32 v246, 0x1200, v246
	v_mul_u32_u24_e32 v247, 0x90, v124
	v_lshl_add_u32 v247, v125, 4, v247
	v_add_u32_e32 v247, v247, v244
	v_mul_u32_u24_e32 v252, 0x50, v124
	v_lshl_add_u32 v252, v125, 3, v252
	v_add_u32_e32 v252, v252, v244
	v_add_u32_e32 v252, 0x1200, v252
	v_add_u32_e32 v253, 0xa00, v252
	v_lshlrev_b32_e32 v244, 4, v176
	v_add_u32_e32 v196, v104, v244
	v_add_u32_e32 v196, 0xe400000, v196
	v_add_u32_e32 v197, 0x400, v196
	v_add_u32_e32 v198, 0x800, v196
	v_add_u32_e32 v199, 0xc00, v196
	v_lshrrev_b32_e32 v244, 2, v176
	v_lshlrev_b32_e32 v195, 4, v195
	v_lshl_add_u32 v200, v244, 10, v195
	v_add_u32_e32 v200, v200, v104
	v_add_u32_e32 v200, 0xe600000, v200
	v_add_u32_e32 v201, 0x4000, v200
	v_add_u32_e32 v202, 0x8000, v200
	v_add_u32_e32 v203, 0xc000, v200
	v_sub_u32_e64 v208, v115, 4 clamp
	v_min_u32_e32 v208, 56, v208
	v_lshlrev_b32_e32 v208, 6, v208
	v_lshl_add_u32 v204, v121, 12, v208
	v_add_u32_e32 v204, 0x1000, v204
	v_lshrrev_b32_e32 v205, 3, v176
	v_add_u32_e32 v204, v204, v205
	v_mul_lo_u32 v204, v204, s19
	v_and_b32_e32 v205, 7, v176
	v_lshlrev_b32_e32 v205, 4, v205
	v_lshl_add_u32 v205, v120, 7, v205
	v_add_u32_e32 v204, v204, v205
	v_add_u32_e32 v204, 0x3d01600, v204
	v_add_u32_e32 v205, 0xe000, v204
	v_add_u32_e32 v206, 0x1c000, v204
	v_add_u32_e32 v207, 0x2a000, v204
	v_lshl_add_u32 v209, v121, 2, v120
	v_lshl_add_u32 v209, v209, 6, v244
	v_lshlrev_b32_e32 v209, 13, v209
	v_lshl_add_u32 v208, v208, 1, v209
	v_add_u32_e32 v208, v208, v195
	v_add_u32_e32 v208, 0xde00000, v208
	v_add_u32_e32 v209, 0x20000, v208
	v_add_u32_e32 v210, 0x40000, v208
	v_add_u32_e32 v211, 0x60000, v208
	global_load_dwordx4 v[212:215], v196, s[56:57]
	global_load_dwordx4 v[216:219], v197, s[56:57]
	global_load_dwordx4 v[220:223], v198, s[56:57]
	global_load_dwordx4 v[224:227], v199, s[56:57]
	global_load_dwordx4 v[228:231], v200, s[56:57]
	global_load_dwordx4 v[232:235], v201, s[56:57]
	global_load_dwordx4 v[236:239], v202, s[56:57]
	global_load_dwordx4 v[240:243], v203, s[56:57]
	v_add_u32_e32 v196, 0x1000, v196
	v_add_u32_e32 v197, 0x1000, v197
	v_add_u32_e32 v198, 0x1000, v198
	v_add_u32_e32 v199, 0x1000, v199
	v_add_u32_e32 v200, 64, v200
	v_add_u32_e32 v201, 64, v201
	v_add_u32_e32 v202, 64, v202
	v_add_u32_e32 v203, 64, v203
	s_waitcnt vmcnt(0)
	ds_write_b128 v245, v[212:215]
	ds_write_b128 v245, v[216:219] offset:1152
	ds_write_b128 v245, v[220:223] offset:2304
	ds_write_b128 v245, v[224:227] offset:3456
	ds_write_b128 v246, v[228:231]
	ds_write_b128 v246, v[232:235] offset:1280
	ds_write_b128 v246, v[236:239] offset:2560
	ds_write_b128 v246, v[240:243] offset:3840
	s_waitcnt lgkmcnt(0)
	global_load_dwordx4 v[212:215], v196, s[56:57]
	global_load_dwordx4 v[216:219], v197, s[56:57]
	global_load_dwordx4 v[220:223], v198, s[56:57]
	global_load_dwordx4 v[224:227], v199, s[56:57]
	global_load_dwordx4 v[228:231], v200, s[56:57]
	global_load_dwordx4 v[232:235], v201, s[56:57]
	global_load_dwordx4 v[236:239], v202, s[56:57]
	global_load_dwordx4 v[240:243], v203, s[56:57]
	v_add_u32_e32 v196, 0x1000, v196
	v_add_u32_e32 v197, 0x1000, v197
	v_add_u32_e32 v198, 0x1000, v198
	v_add_u32_e32 v199, 0x1000, v199
	v_add_u32_e32 v200, 64, v200
	v_add_u32_e32 v201, 64, v201
	v_add_u32_e32 v202, 64, v202
	v_add_u32_e32 v203, 64, v203
.LBB0_221:
	v_mov_b32_e32 v0, v118
	v_mov_b32_e32 v97, v123
	s_add_i32 s0, s0, -1
	ds_read_b128 v[248:251], v247
	ds_read_b128 v[126:129], v247 offset:32
	ds_read_b128 v[134:137], v247 offset:64
	ds_read_b128 v[138:141], v247 offset:96
	ds_read2_b64 v[78:81], v252 offset1:2
	ds_read2_b64 v[74:77], v253 offset1:2
	ds_read2_b64 v[70:73], v252 offset0:4 offset1:6
	ds_read2_b64 v[66:69], v253 offset0:4 offset1:6
	s_waitcnt vmcnt(0)
	ds_write_b128 v245, v[212:215]
	ds_write_b128 v245, v[216:219] offset:1152
	ds_write_b128 v245, v[220:223] offset:2304
	ds_write_b128 v245, v[224:227] offset:3456
	ds_write_b128 v246, v[228:231]
	ds_write_b128 v246, v[232:235] offset:1280
	ds_write_b128 v246, v[236:239] offset:2560
	ds_write_b128 v246, v[240:243] offset:3840
	s_waitcnt lgkmcnt(8)
	v_mfma_f32_32x32x16_bf16 v[34:49], v[248:251], v[58:61], 0
	v_mfma_f32_32x32x16_bf16 v[34:49], v[126:129], v[50:53], v[34:49]
	v_mfma_f32_32x32x16_bf16 v[34:49], v[134:137], v[54:57], v[34:49]
	v_mfma_f32_32x32x16_bf16 v[34:49], v[138:141], v[62:65], v[34:49]
	s_waitcnt lgkmcnt(0)
	s_cmp_lt_u32 s0, 2
	s_cbranch_scc1 .Lnb_ld_local
	global_load_dwordx4 v[212:215], v196, s[56:57]
	global_load_dwordx4 v[216:219], v197, s[56:57]
	global_load_dwordx4 v[220:223], v198, s[56:57]
	global_load_dwordx4 v[224:227], v199, s[56:57]
	global_load_dwordx4 v[228:231], v200, s[56:57]
	global_load_dwordx4 v[232:235], v201, s[56:57]
	global_load_dwordx4 v[236:239], v202, s[56:57]
	global_load_dwordx4 v[240:243], v203, s[56:57]
	v_add_u32_e32 v196, 0x1000, v196
	v_add_u32_e32 v197, 0x1000, v197
	v_add_u32_e32 v198, 0x1000, v198
	v_add_u32_e32 v199, 0x1000, v199
	v_add_u32_e32 v200, 64, v200
	v_add_u32_e32 v201, 64, v201
	v_add_u32_e32 v202, 64, v202
	v_add_u32_e32 v203, 64, v203
	s_branch .Lnb_ld_done
.Lnb_ld_local:
	global_load_dwordx4 v[212:215], v204, s[56:57]
	global_load_dwordx4 v[216:219], v205, s[56:57]
	global_load_dwordx4 v[220:223], v206, s[56:57]
	global_load_dwordx4 v[224:227], v207, s[56:57]
	global_load_dwordx4 v[228:231], v208, s[56:57]
	global_load_dwordx4 v[232:235], v209, s[56:57]
	global_load_dwordx4 v[236:239], v210, s[56:57]
	global_load_dwordx4 v[240:243], v211, s[56:57]
	v_add_u32_e32 v204, 0x38000, v204
	v_add_u32_e32 v205, 0x38000, v205
	v_add_u32_e32 v206, 0x38000, v206
	v_add_u32_e32 v207, 0x38000, v207
	v_add_u32_e32 v208, 64, v208
	v_add_u32_e32 v209, 64, v209
	v_add_u32_e32 v210, 64, v210
	v_add_u32_e32 v211, 64, v211
.Lnb_ld_done:
	v_mul_f32_e32 v118, 0x3e38aa3b, v34
	v_mul_f32_e32 v119, 0x3e38aa3b, v35
	v_max3_f32 v118, v118, s52, v119
	v_mul_f32_e32 v119, 0x3e38aa3b, v36
	v_mul_f32_e32 v123, 0x3e38aa3b, v37
	v_max3_f32 v118, v118, v119, v123
	v_mul_f32_e32 v119, 0x3e38aa3b, v38
	v_mul_f32_e32 v123, 0x3e38aa3b, v39
	v_max3_f32 v118, v118, v119, v123
	v_mul_f32_e32 v119, 0x3e38aa3b, v40
	v_mul_f32_e32 v123, 0x3e38aa3b, v41
	v_max3_f32 v118, v118, v119, v123
	v_mul_f32_e32 v119, 0x3e38aa3b, v42
	v_mul_f32_e32 v123, 0x3e38aa3b, v43
	v_max3_f32 v118, v118, v119, v123
	v_mul_f32_e32 v119, 0x3e38aa3b, v44
	v_mul_f32_e32 v123, 0x3e38aa3b, v45
	v_max3_f32 v118, v118, v119, v123
	v_mul_f32_e32 v119, 0x3e38aa3b, v46
	v_mul_f32_e32 v123, 0x3e38aa3b, v47
	v_max3_f32 v118, v118, v119, v123
	v_mul_f32_e32 v119, 0x3e38aa3b, v48
	v_mul_f32_e32 v123, 0x3e38aa3b, v49
	v_max3_f32 v118, v118, v119, v123
	ds_bpermute_b32 v119, v117, v118
	s_waitcnt lgkmcnt(0)
	v_max3_f32 v118, v0, v118, v119
	v_fma_f32 v34, v34, s18, -v118
	v_exp_f32_e32 v34, v34
	v_fma_f32 v35, v35, s18, -v118
	v_exp_f32_e32 v35, v35
	v_fma_f32 v36, v36, s18, -v118
	v_exp_f32_e32 v36, v36
	v_fma_f32 v37, v37, s18, -v118
	v_exp_f32_e32 v37, v37
	v_fma_f32 v38, v38, s18, -v118
	v_add_f32_e32 v119, 0, v34
	v_exp_f32_e32 v38, v38
	v_fma_f32 v39, v39, s18, -v118
	v_sub_f32_e32 v0, v0, v118
	v_add_f32_e32 v119, v35, v119
	v_exp_f32_e32 v39, v39
	v_fma_f32 v40, v40, s18, -v118
	v_fma_f32 v41, v41, s18, -v118
	v_add_f32_e32 v119, v36, v119
	v_exp_f32_e32 v40, v40
	v_exp_f32_e32 v41, v41
	v_exp_f32_e32 v0, v0
	v_add_f32_e32 v119, v37, v119
	v_fma_f32 v42, v42, s18, -v118
	v_add_f32_e32 v119, v38, v119
	v_exp_f32_e32 v42, v42
	v_fma_f32 v43, v43, s18, -v118
	v_add_f32_e32 v119, v39, v119
	v_exp_f32_e32 v43, v43
	v_fma_f32 v44, v44, s18, -v118
	v_add_f32_e32 v119, v40, v119
	v_exp_f32_e32 v44, v44
	v_fma_f32 v45, v45, s18, -v118
	v_pk_mul_f32 v[32:33], v[32:33], v[0:1] op_sel_hi:[1,0]
	v_pk_mul_f32 v[30:31], v[30:31], v[0:1] op_sel_hi:[1,0]
	v_pk_mul_f32 v[28:29], v[28:29], v[0:1] op_sel_hi:[1,0]
	v_pk_mul_f32 v[26:27], v[26:27], v[0:1] op_sel_hi:[1,0]
	v_pk_mul_f32 v[24:25], v[24:25], v[0:1] op_sel_hi:[1,0]
	v_pk_mul_f32 v[22:23], v[22:23], v[0:1] op_sel_hi:[1,0]
	v_pk_mul_f32 v[20:21], v[20:21], v[0:1] op_sel_hi:[1,0]
	v_pk_mul_f32 v[18:19], v[18:19], v[0:1] op_sel_hi:[1,0]
	v_pk_mul_f32 v[16:17], v[16:17], v[0:1] op_sel_hi:[1,0]
	v_pk_mul_f32 v[14:15], v[14:15], v[0:1] op_sel_hi:[1,0]
	v_pk_mul_f32 v[12:13], v[12:13], v[0:1] op_sel_hi:[1,0]
	v_pk_mul_f32 v[10:11], v[10:11], v[0:1] op_sel_hi:[1,0]
	v_pk_mul_f32 v[8:9], v[8:9], v[0:1] op_sel_hi:[1,0]
	v_pk_mul_f32 v[6:7], v[6:7], v[0:1] op_sel_hi:[1,0]
	v_pk_mul_f32 v[4:5], v[4:5], v[0:1] op_sel_hi:[1,0]
	v_pk_mul_f32 v[2:3], v[2:3], v[0:1] op_sel_hi:[1,0]
	v_cvt_pk_bf16_f32 v34, v34, v35
	v_cvt_pk_bf16_f32 v35, v36, v37
	v_cvt_pk_bf16_f32 v36, v38, v39
	v_cvt_pk_bf16_f32 v37, v40, v41
	v_add_f32_e32 v119, v41, v119
	v_exp_f32_e32 v45, v45
	v_fma_f32 v46, v46, s18, -v118
	s_nop 0
	v_mfma_f32_32x32x16_bf16 v[18:33], v[78:81], v[34:37], v[18:33]
	v_add_f32_e32 v119, v42, v119
	v_exp_f32_e32 v46, v46
	v_fma_f32 v47, v47, s18, -v118
	v_add_f32_e32 v119, v43, v119
	v_exp_f32_e32 v47, v47
	v_fma_f32 v48, v48, s18, -v118
	v_fma_f32 v49, v49, s18, -v118
	s_nop 0
	v_mfma_f32_32x32x16_bf16 v[2:17], v[74:77], v[34:37], v[2:17]
	v_add_f32_e32 v119, v44, v119
	v_exp_f32_e32 v48, v48
	v_exp_f32_e32 v49, v49
	v_add_f32_e32 v119, v45, v119
	v_add_f32_e32 v119, v46, v119
	v_add_f32_e32 v119, v47, v119
	v_add_f32_e32 v119, v48, v119
	v_cvt_pk_bf16_f32 v34, v42, v43
	v_cvt_pk_bf16_f32 v35, v44, v45
	v_cvt_pk_bf16_f32 v36, v46, v47
	v_cvt_pk_bf16_f32 v37, v48, v49
	v_add_f32_e32 v119, v49, v119
	ds_bpermute_b32 v123, v117, v119
	v_mfma_f32_32x32x16_bf16 v[18:33], v[70:73], v[34:37], v[18:33]
	s_waitcnt lgkmcnt(0)
	v_add_f32_e32 v123, v119, v123
	v_fmac_f32_e32 v123, v97, v0
	v_mfma_f32_32x32x16_bf16 v[2:17], v[66:69], v[34:37], v[2:17]
	s_cmp_eq_u32 s0, 0
	s_cbranch_scc0 .LBB0_221
	v_sub_u32_e64 v0, v115, 4 clamp
	v_min_u32_e32 v105, 56, v0
	v_max_i32_e32 v0, 8, v116
	v_add_u32_e32 v0, -8, v0
	v_min_u32_e32 v119, 48, v0
	v_lshlrev_b32_e32 v0, 8, v121
	v_or3_b32 v0, v0, v100, v124
	s_movk_i32 s0, 0x744
	v_lshlrev_b64 v[34:35], 13, v[0:1]
	v_mad_u32_u24 v104, v120, s0, 0
	v_or_b32_e32 v120, v122, v124
	v_lshl_add_u64 v[106:107], v[86:87], 0, v[34:35]
	v_add_u32_e32 v121, 16, v119
	s_mov_b32 s0, 0
	s_mov_b32 s1, 0
.LBB0_223:
	s_lshr_b32 s2, s1, 1
	v_add_u32_e32 v0, s2, v105
	s_and_b32 s2, s0, 32
	v_sub_u32_e32 v0, v0, v115
	s_movk_i32 s4, 0x7c
	v_mad_u64_u32 v[108:109], s[4:5], v0, s4, v[104:105]
	v_lshlrev_b32_e32 v0, 1, v100
	v_or_b32_e32 v109, s2, v82
	v_cmp_ge_u32_e32 vcc, v109, v119
	v_cmp_lt_u32_e64 s[4:5], v109, v121
	v_sub_u32_e32 v97, v109, v116
	s_and_b64 vcc, vcc, s[4:5]
	v_add_u32_e32 v97, 15, v97
	v_cndmask_b32_e32 v97, 0, v97, vcc
	v_lshl_add_u32 v97, v97, 2, v108
	ds_read_b32 v97, v97 offset:868
	v_mov_b32_e32 v122, v123
	v_or_b32_e32 v123, 2, v109
	s_add_i32 s1, s1, 1
	s_add_i32 s0, s0, 32
	ds_read_b128 v[248:251], v247
	ds_read_b128 v[126:129], v247 offset:32
	ds_read_b128 v[134:137], v247 offset:64
	ds_read_b128 v[138:141], v247 offset:96
	ds_read2_b64 v[78:81], v252 offset1:2
	ds_read2_b64 v[74:77], v253 offset1:2
	ds_read2_b64 v[70:73], v252 offset0:4 offset1:6
	ds_read2_b64 v[66:69], v253 offset0:4 offset1:6
	s_waitcnt vmcnt(0)
	ds_write_b128 v245, v[212:215]
	ds_write_b128 v245, v[216:219] offset:1152
	ds_write_b128 v245, v[220:223] offset:2304
	ds_write_b128 v245, v[224:227] offset:3456
	ds_write_b128 v246, v[228:231]
	ds_write_b128 v246, v[232:235] offset:1280
	ds_write_b128 v246, v[236:239] offset:2560
	ds_write_b128 v246, v[240:243] offset:3840
	s_waitcnt lgkmcnt(8)
	v_mfma_f32_32x32x16_bf16 v[34:49], v[248:251], v[58:61], 0
	v_mfma_f32_32x32x16_bf16 v[34:49], v[126:129], v[50:53], v[34:49]
	v_mfma_f32_32x32x16_bf16 v[34:49], v[134:137], v[54:57], v[34:49]
	v_mfma_f32_32x32x16_bf16 v[34:49], v[138:141], v[62:65], v[34:49]
	s_waitcnt lgkmcnt(0)
	s_cmp_ge_u32 s1, 31
	s_cbranch_scc1 .Lnb_l_skip
	global_load_dwordx4 v[212:215], v204, s[56:57]
	global_load_dwordx4 v[216:219], v205, s[56:57]
	global_load_dwordx4 v[220:223], v206, s[56:57]
	global_load_dwordx4 v[224:227], v207, s[56:57]
	global_load_dwordx4 v[228:231], v208, s[56:57]
	global_load_dwordx4 v[232:235], v209, s[56:57]
	global_load_dwordx4 v[236:239], v210, s[56:57]
	global_load_dwordx4 v[240:243], v211, s[56:57]
	v_add_u32_e32 v204, 0x38000, v204
	v_add_u32_e32 v205, 0x38000, v205
	v_add_u32_e32 v206, 0x38000, v206
	v_add_u32_e32 v207, 0x38000, v207
	v_add_u32_e32 v208, 64, v208
	v_add_u32_e32 v209, 64, v209
	v_add_u32_e32 v210, 64, v210
	v_add_u32_e32 v211, 64, v211
	s_branch .Lnb_l_cont
.Lnb_l_skip:
	s_nop 9
.Lnb_l_cont:
	v_fmac_f32_e32 v97, 0x3e38aa3b, v34
	v_cndmask_b32_e32 v34, v186, v97, vcc
	v_or_b32_e32 v97, 1, v109
	v_cmp_ge_u32_e32 vcc, v97, v119
	v_cmp_lt_u32_e64 s[4:5], v97, v121
	v_sub_u32_e32 v97, v97, v116
	s_and_b64 vcc, vcc, s[4:5]
	v_add_u32_e32 v97, 15, v97
	v_cndmask_b32_e32 v97, 0, v97, vcc
	v_lshl_add_u32 v97, v97, 2, v108
	ds_read_b32 v97, v97 offset:868
	v_cmp_lt_u32_e64 s[4:5], v123, v121
	s_waitcnt lgkmcnt(0)
	v_fmac_f32_e32 v97, 0x3e38aa3b, v35
	v_cndmask_b32_e32 v35, v186, v97, vcc
	v_cmp_ge_u32_e32 vcc, v123, v119
	v_sub_u32_e32 v123, v123, v116
	s_and_b64 vcc, vcc, s[4:5]
	v_add_u32_e32 v123, 15, v123
	v_cndmask_b32_e32 v123, 0, v123, vcc
	v_lshl_add_u32 v123, v123, 2, v108
	ds_read_b32 v123, v123 offset:868
	v_max3_f32 v97, v34, s52, v35
	s_waitcnt lgkmcnt(0)
	v_fmac_f32_e32 v123, 0x3e38aa3b, v36
	v_cndmask_b32_e32 v36, v186, v123, vcc
	v_or_b32_e32 v123, 3, v109
	v_cmp_ge_u32_e32 vcc, v123, v119
	v_cmp_lt_u32_e64 s[4:5], v123, v121
	v_sub_u32_e32 v123, v123, v116
	s_and_b64 vcc, vcc, s[4:5]
	v_add_u32_e32 v123, 15, v123
	v_cndmask_b32_e32 v123, 0, v123, vcc
	v_lshl_add_u32 v123, v123, 2, v108
	ds_read_b32 v123, v123 offset:868
	s_waitcnt lgkmcnt(0)
	v_fmac_f32_e32 v123, 0x3e38aa3b, v37
	v_cndmask_b32_e32 v37, v186, v123, vcc
	v_or_b32_e32 v123, 8, v109
	v_cmp_ge_u32_e32 vcc, v123, v119
	v_cmp_lt_u32_e64 s[4:5], v123, v121
	v_sub_u32_e32 v123, v123, v116
	s_and_b64 vcc, vcc, s[4:5]
	v_add_u32_e32 v123, 15, v123
	v_cndmask_b32_e32 v123, 0, v123, vcc
	v_lshl_add_u32 v123, v123, 2, v108
	ds_read_b32 v123, v123 offset:868
	v_max3_f32 v97, v97, v36, v37
	s_waitcnt lgkmcnt(0)
	v_fmac_f32_e32 v123, 0x3e38aa3b, v38
	v_cndmask_b32_e32 v38, v186, v123, vcc
	v_or_b32_e32 v123, 9, v109
	v_cmp_ge_u32_e32 vcc, v123, v119
	v_cmp_lt_u32_e64 s[4:5], v123, v121
	v_sub_u32_e32 v123, v123, v116
	s_and_b64 vcc, vcc, s[4:5]
	v_add_u32_e32 v123, 15, v123
	v_cndmask_b32_e32 v123, 0, v123, vcc
	v_lshl_add_u32 v123, v123, 2, v108
	ds_read_b32 v123, v123 offset:868
	s_waitcnt lgkmcnt(0)
	v_fmac_f32_e32 v123, 0x3e38aa3b, v39
	v_cndmask_b32_e32 v39, v186, v123, vcc
	v_or_b32_e32 v123, 10, v109
	v_cmp_ge_u32_e32 vcc, v123, v119
	v_cmp_lt_u32_e64 s[4:5], v123, v121
	v_sub_u32_e32 v123, v123, v116
	s_and_b64 vcc, vcc, s[4:5]
	v_add_u32_e32 v123, 15, v123
	v_cndmask_b32_e32 v123, 0, v123, vcc
	v_lshl_add_u32 v123, v123, 2, v108
	ds_read_b32 v123, v123 offset:868
	v_max3_f32 v97, v97, v38, v39
	s_waitcnt lgkmcnt(0)
	v_fmac_f32_e32 v123, 0x3e38aa3b, v40
	v_cndmask_b32_e32 v40, v186, v123, vcc
	v_or_b32_e32 v123, 11, v109
	v_cmp_ge_u32_e32 vcc, v123, v119
	v_cmp_lt_u32_e64 s[4:5], v123, v121
	v_sub_u32_e32 v123, v123, v116
	s_and_b64 vcc, vcc, s[4:5]
	v_add_u32_e32 v123, 15, v123
	v_cndmask_b32_e32 v123, 0, v123, vcc
	v_lshl_add_u32 v123, v123, 2, v108
	ds_read_b32 v123, v123 offset:868
	v_cmp_lt_u32_e64 s[4:5], v109, v119
	s_waitcnt lgkmcnt(0)
	v_fmac_f32_e32 v123, 0x3e38aa3b, v41
	v_cndmask_b32_e32 v41, v186, v123, vcc
	v_or_b32_e32 v123, 16, v109
	v_cmp_ge_u32_e32 vcc, v123, v119
	v_sub_u32_e32 v123, v123, v116
	s_and_b64 vcc, vcc, s[4:5]
	v_add_u32_e32 v123, 15, v123
	v_cndmask_b32_e32 v123, 0, v123, vcc
	v_lshl_add_u32 v123, v123, 2, v108
	ds_read_b32 v123, v123 offset:868
	v_max3_f32 v97, v97, v40, v41
	s_waitcnt lgkmcnt(0)
	v_fmac_f32_e32 v123, 0x3e38aa3b, v42
	v_cndmask_b32_e32 v42, v186, v123, vcc
	v_or_b32_e32 v123, 17, v109
	v_cmp_ge_u32_e32 vcc, v123, v119
	v_cmp_lt_u32_e64 s[4:5], v123, v121
	v_sub_u32_e32 v123, v123, v116
	s_and_b64 vcc, vcc, s[4:5]
	v_add_u32_e32 v123, 15, v123
	v_cndmask_b32_e32 v123, 0, v123, vcc
	v_lshl_add_u32 v123, v123, 2, v108
	ds_read_b32 v123, v123 offset:868
	s_waitcnt lgkmcnt(0)
	v_fmac_f32_e32 v123, 0x3e38aa3b, v43
	v_cndmask_b32_e32 v43, v186, v123, vcc
	v_or_b32_e32 v123, 18, v109
	v_cmp_ge_u32_e32 vcc, v123, v119
	v_cmp_lt_u32_e64 s[4:5], v123, v121
	v_sub_u32_e32 v123, v123, v116
	s_and_b64 vcc, vcc, s[4:5]
	v_add_u32_e32 v123, 15, v123
	v_cndmask_b32_e32 v123, 0, v123, vcc
	v_lshl_add_u32 v123, v123, 2, v108
	ds_read_b32 v123, v123 offset:868
	v_max3_f32 v97, v97, v42, v43
	s_waitcnt lgkmcnt(0)
	v_fmac_f32_e32 v123, 0x3e38aa3b, v44
	v_cndmask_b32_e32 v44, v186, v123, vcc
	v_or_b32_e32 v123, 19, v109
	v_cmp_ge_u32_e32 vcc, v123, v119
	v_cmp_lt_u32_e64 s[4:5], v123, v121
	v_sub_u32_e32 v123, v123, v116
	s_and_b64 vcc, vcc, s[4:5]
	v_add_u32_e32 v123, 15, v123
	v_cndmask_b32_e32 v123, 0, v123, vcc
	v_lshl_add_u32 v123, v123, 2, v108
	ds_read_b32 v123, v123 offset:868
	s_waitcnt lgkmcnt(0)
	v_fmac_f32_e32 v123, 0x3e38aa3b, v45
	v_cndmask_b32_e32 v45, v186, v123, vcc
	v_or_b32_e32 v123, 24, v109
	v_cmp_ge_u32_e32 vcc, v123, v119
	v_cmp_lt_u32_e64 s[4:5], v123, v121
	v_sub_u32_e32 v123, v123, v116
	s_and_b64 vcc, vcc, s[4:5]
	v_add_u32_e32 v123, 15, v123
	v_cndmask_b32_e32 v123, 0, v123, vcc
	v_lshl_add_u32 v123, v123, 2, v108
	ds_read_b32 v123, v123 offset:868
	v_max3_f32 v97, v97, v44, v45
	s_waitcnt lgkmcnt(0)
	v_fmac_f32_e32 v123, 0x3e38aa3b, v46
	v_cndmask_b32_e32 v46, v186, v123, vcc
	v_or_b32_e32 v123, 25, v109
	v_cmp_ge_u32_e32 vcc, v123, v119
	v_cmp_lt_u32_e64 s[4:5], v123, v121
	v_sub_u32_e32 v123, v123, v116
	s_and_b64 vcc, vcc, s[4:5]
	v_add_u32_e32 v123, 15, v123
	v_cndmask_b32_e32 v123, 0, v123, vcc
	v_lshl_add_u32 v123, v123, 2, v108
	ds_read_b32 v123, v123 offset:868
	s_waitcnt lgkmcnt(0)
	v_fmac_f32_e32 v123, 0x3e38aa3b, v47
	v_cndmask_b32_e32 v47, v186, v123, vcc
	v_or_b32_e32 v123, 26, v109
	v_cmp_ge_u32_e32 vcc, v123, v119
	v_cmp_lt_u32_e64 s[4:5], v123, v121
	v_sub_u32_e32 v123, v123, v116
	s_and_b64 vcc, vcc, s[4:5]
	v_add_u32_e32 v123, 15, v123
	v_cndmask_b32_e32 v123, 0, v123, vcc
	v_lshl_add_u32 v123, v123, 2, v108
	ds_read_b32 v123, v123 offset:868
	v_or_b32_e32 v109, 27, v109
	v_cmp_lt_u32_e64 s[4:5], v109, v121
	v_max3_f32 v97, v97, v46, v47
	s_waitcnt lgkmcnt(0)
	v_fmac_f32_e32 v123, 0x3e38aa3b, v48
	v_cndmask_b32_e32 v48, v186, v123, vcc
	v_cmp_ge_u32_e32 vcc, v109, v119
	v_sub_u32_e32 v109, v109, v116
	s_and_b64 vcc, vcc, s[4:5]
	v_add_u32_e32 v109, 15, v109
	v_cndmask_b32_e32 v109, 0, v109, vcc
	v_lshl_add_u32 v108, v109, 2, v108
	ds_read_b32 v108, v108 offset:868
	s_cmp_eq_u32 s1, 16
	s_waitcnt lgkmcnt(0)
	v_fmac_f32_e32 v108, 0x3e38aa3b, v49
	v_cndmask_b32_e32 v49, v186, v108, vcc
	v_max3_f32 v97, v97, v48, v49
	ds_bpermute_b32 v108, v117, v97
	s_waitcnt lgkmcnt(0)
	v_max3_f32 v97, v118, v97, v108
	v_sub_f32_e32 v34, v34, v97
	v_exp_f32_e32 v109, v34
	v_sub_f32_e32 v35, v35, v97
	v_exp_f32_e32 v35, v35
	v_sub_f32_e32 v36, v36, v97
	v_exp_f32_e32 v36, v36
	v_sub_f32_e32 v37, v37, v97
	v_exp_f32_e32 v37, v37
	v_sub_f32_e32 v38, v38, v97
	v_add_f32_e32 v34, 0, v109
	v_exp_f32_e32 v38, v38
	v_sub_f32_e32 v39, v39, v97
	v_add_f32_e32 v34, v35, v34
	v_exp_f32_e32 v39, v39
	v_sub_f32_e32 v40, v40, v97
	v_add_f32_e32 v34, v36, v34
	v_exp_f32_e32 v40, v40
	v_sub_f32_e32 v41, v41, v97
	v_add_f32_e32 v34, v37, v34
	v_exp_f32_e32 v41, v41
	v_sub_f32_e32 v42, v42, v97
	v_add_f32_e32 v34, v38, v34
	v_exp_f32_e32 v42, v42
	v_sub_f32_e32 v43, v43, v97
	v_add_f32_e32 v34, v39, v34
	v_exp_f32_e32 v43, v43
	v_sub_f32_e32 v44, v44, v97
	v_add_f32_e32 v34, v40, v34
	v_exp_f32_e32 v44, v44
	v_sub_f32_e32 v45, v45, v97
	v_add_f32_e32 v34, v41, v34
	v_exp_f32_e32 v45, v45
	v_sub_f32_e32 v46, v46, v97
	v_add_f32_e32 v34, v42, v34
	v_exp_f32_e32 v46, v46
	v_sub_f32_e32 v47, v47, v97
	v_add_f32_e32 v34, v43, v34
	v_exp_f32_e32 v47, v47
	v_sub_f32_e32 v48, v48, v97
	v_add_f32_e32 v34, v44, v34
	v_exp_f32_e32 v48, v48
	v_sub_f32_e32 v49, v49, v97
	v_add_f32_e32 v34, v45, v34
	v_exp_f32_e32 v49, v49
	v_add_f32_e32 v34, v46, v34
	v_add_f32_e32 v34, v47, v34
	v_add_f32_e32 v34, v48, v34
	v_sub_f32_e32 v108, v118, v97
	v_add_f32_e32 v118, v49, v34
	v_exp_f32_e32 v34, v108
	ds_bpermute_b32 v108, v117, v118
	v_pk_mul_f32 v[32:33], v[32:33], v[34:35] op_sel_hi:[1,0]
	v_pk_mul_f32 v[30:31], v[30:31], v[34:35] op_sel_hi:[1,0]
	s_waitcnt lgkmcnt(0)
	v_add_f32_e32 v123, v118, v108
	v_fmac_f32_e32 v123, v122, v34
	v_pk_mul_f32 v[28:29], v[28:29], v[34:35] op_sel_hi:[1,0]
	v_pk_mul_f32 v[26:27], v[26:27], v[34:35] op_sel_hi:[1,0]
	v_pk_mul_f32 v[24:25], v[24:25], v[34:35] op_sel_hi:[1,0]
	v_pk_mul_f32 v[22:23], v[22:23], v[34:35] op_sel_hi:[1,0]
	v_pk_mul_f32 v[20:21], v[20:21], v[34:35] op_sel_hi:[1,0]
	v_pk_mul_f32 v[18:19], v[18:19], v[34:35] op_sel_hi:[1,0]
	v_pk_mul_f32 v[16:17], v[16:17], v[34:35] op_sel_hi:[1,0]
	v_pk_mul_f32 v[14:15], v[14:15], v[34:35] op_sel_hi:[1,0]
	v_pk_mul_f32 v[12:13], v[12:13], v[34:35] op_sel_hi:[1,0]
	v_pk_mul_f32 v[10:11], v[10:11], v[34:35] op_sel_hi:[1,0]
	v_pk_mul_f32 v[8:9], v[8:9], v[34:35] op_sel_hi:[1,0]
	v_pk_mul_f32 v[6:7], v[6:7], v[34:35] op_sel_hi:[1,0]
	v_pk_mul_f32 v[4:5], v[4:5], v[34:35] op_sel_hi:[1,0]
	v_pk_mul_f32 v[2:3], v[2:3], v[34:35] op_sel_hi:[1,0]
	v_cvt_pk_bf16_f32 v34, v109, v35
	v_cvt_pk_bf16_f32 v35, v36, v37
	v_cvt_pk_bf16_f32 v36, v38, v39
	v_cvt_pk_bf16_f32 v37, v40, v41
	v_mov_b32_e32 v118, v97
	s_nop 0
	v_mfma_f32_32x32x16_bf16 v[18:33], v[78:81], v[34:37], v[18:33]
	s_nop 0
	v_mfma_f32_32x32x16_bf16 v[2:17], v[74:77], v[34:37], v[2:17]
	v_cvt_pk_bf16_f32 v34, v42, v43
	v_cvt_pk_bf16_f32 v35, v44, v45
	v_cvt_pk_bf16_f32 v36, v46, v47
	v_cvt_pk_bf16_f32 v37, v48, v49
	s_nop 1
	v_mfma_f32_32x32x16_bf16 v[18:33], v[70:73], v[34:37], v[18:33]
	s_nop 0
	v_mfma_f32_32x32x16_bf16 v[2:17], v[66:69], v[34:37], v[2:17]
	s_cbranch_scc0 .LBB0_223
	v_lshl_add_u64 v[34:35], v[102:103], 0, v[0:1]
	s_mov_b64 s[0:1], 0x1a00
	v_lshl_add_u64 v[36:37], v[34:35], 0, s[0:1]
